# v64 + grid barrier: this CU's early L1/L2 invalidate issued after the arrival atomic instead of before it
# speedup vs baseline: 1.0152x; 1.0010x over previous
.LBB0_411:
	global_atomic_add v3, v[140:141], v166, off sc0
	buffer_inv sc1
	v_cvt_f32_u32_e32 v1, v2
	v_sub_u32_e32 v4, 0, v2
	v_rcp_iflag_f32_e32 v1, v1
	s_nop 0
	v_mul_f32_e32 v1, 0x4f7ffffe, v1
	v_cvt_u32_f32_e32 v1, v1
	v_mul_lo_u32 v4, v4, v1
	v_mul_hi_u32 v4, v1, v4
	v_add_u32_e32 v1, v1, v4
	s_waitcnt vmcnt(0)
	v_mul_hi_u32 v1, v3, v1
	v_mul_lo_u32 v4, v1, v2
	v_sub_u32_e32 v4, v3, v4
	v_add_u32_e32 v5, 1, v1
	v_cmp_ge_u32_e32 vcc, v4, v2
	v_add_u32_e32 v3, 1, v3
	s_nop 0
	v_cndmask_b32_e32 v1, v1, v5, vcc
	v_sub_u32_e32 v5, v4, v2
	v_cndmask_b32_e32 v4, v4, v5, vcc
	v_add_u32_e32 v5, 1, v1
	v_cmp_ge_u32_e32 vcc, v4, v2
	s_nop 1
	v_cndmask_b32_e32 v1, v1, v5, vcc
	v_mul_lo_u32 v4, v2, v1
	v_add_u32_e32 v2, v4, v2
	v_cmp_ne_u32_e32 vcc, v3, v2
	s_and_saveexec_b64 s[2:3], vcc
	s_xor_b64 s[2:3], exec, s[2:3]
	s_cbranch_execz .LBB0_425
	s_waitcnt lgkmcnt(0)
	global_load_dword v0, v[142:143], off sc1
	s_waitcnt vmcnt(0)
	v_cmp_eq_u32_e32 vcc, v0, v1
	s_and_saveexec_b64 s[4:5], vcc
	s_cbranch_execz .LBB0_424
	s_mov_b32 s12, 1
	s_mov_b64 s[6:7], 0
	s_branch .LBB0_415

.LBB0_1393:
	global_atomic_add v3, v[140:141], v166, off sc0
	buffer_inv sc1
	v_cvt_f32_u32_e32 v1, v2
	v_sub_u32_e32 v4, 0, v2
	v_rcp_iflag_f32_e32 v1, v1
	s_nop 0
	v_mul_f32_e32 v1, 0x4f7ffffe, v1
	v_cvt_u32_f32_e32 v1, v1
	v_mul_lo_u32 v4, v4, v1
	v_mul_hi_u32 v4, v1, v4
	v_add_u32_e32 v1, v1, v4
	s_waitcnt vmcnt(0)
	v_mul_hi_u32 v1, v3, v1
	v_mul_lo_u32 v4, v1, v2
	v_sub_u32_e32 v4, v3, v4
	v_add_u32_e32 v5, 1, v1
	v_cmp_ge_u32_e32 vcc, v4, v2
	v_add_u32_e32 v3, 1, v3
	s_nop 0
	v_cndmask_b32_e32 v1, v1, v5, vcc
	v_sub_u32_e32 v5, v4, v2
	v_cndmask_b32_e32 v4, v4, v5, vcc
	v_add_u32_e32 v5, 1, v1
	v_cmp_ge_u32_e32 vcc, v4, v2
	s_nop 1
	v_cndmask_b32_e32 v1, v1, v5, vcc
	v_mul_lo_u32 v4, v2, v1
	v_add_u32_e32 v2, v4, v2
	v_cmp_ne_u32_e32 vcc, v3, v2
	s_and_saveexec_b64 s[4:5], vcc
	s_xor_b64 s[4:5], exec, s[4:5]
	s_cbranch_execz .LBB0_1407
	s_waitcnt lgkmcnt(0)
	global_load_dword v0, v[142:143], off sc1
	s_waitcnt vmcnt(0)
	v_cmp_eq_u32_e32 vcc, v0, v1
	s_and_saveexec_b64 s[6:7], vcc
	s_cbranch_execz .LBB0_1406
	s_mov_b32 s1, 1
	s_mov_b64 s[8:9], 0
	s_branch .LBB0_1397
